# W_in: rowss loads issued at the top of each unit (before its K-loop); epilogue has no load and no wait
# baseline (speedup 1.0000x reference)
;     __host__ __device__ bool next(int i, Unit& u) const {
;         const long L = (long)i * G + c; if (L >= nwg) return false;
;         int wgid = (int)L; { const int q = nwg / NXCD, r = nwg % NXCD, xcd = wgid % NXCD, off = wgid / NXCD; wgid = (xcd < r ? xcd * (q + 1) : r * (q + 1) + (xcd - r) * q) + off; }
;         const int nig = WGM * nN, gid = wgid / nig, fm = gid * WGM, gsz = (nM - fm) < WGM ? (nM - fm) : WGM;
;         u.pm = fm + ((wgid % nig) % gsz); u.pn = (wgid % nig) / gsz; return true;
; template <class Epi, class Sched, bool ALIGN_EPI = false, bool SP2 = false>
; __device__ __forceinline__ void gemm_phase(PG8_LAS unsigned char* lds, const Gemm g, const Sched& S, const Epi& E) {
;     ...
;     for (;;) {
;         const bool has_next = S.next(ui + 1, nxt);
;         const char* nA = has_next ? (const char*)g.A + (size_t)nxt.pm * tstep : cA; const char* nB = has_next ? (const char*)g.Bt + (size_t)nxt.pn * tstep : cB;
.LBB0_407:
	v_lshl_add_u32 v238, s16, 8, v152
	v_ashrrev_i32_e32 v239, 31, v238
	v_lshl_add_u64 v[238:239], v[238:239], 2, s[20:21]
	global_load_dword v237, v[238:239], off
	global_load_dword v230, v[238:239], off offset:64
	global_load_dword v231, v[238:239], off offset:128
	global_load_dword v232, v[238:239], off offset:192
	global_load_dword v233, v[238:239], off offset:512
	global_load_dword v234, v[238:239], off offset:576
	global_load_dword v235, v[238:239], off offset:640
	global_load_dword v236, v[238:239], off offset:704
	s_add_i32 s38, s38, 1
	s_mul_i32 s2, s38, s39
	s_mul_hi_u32 s3, s38, s42
	s_add_i32 s3, s3, s2
	s_mul_i32 s2, s38, s42
	s_add_u32 s12, s2, s33
	s_addc_u32 s13, s3, s31
	v_cmp_gt_i64_e32 vcc, s[12:13], v[142:143]
	v_cmp_lt_i64_e64 s[2:3], s[12:13], v[140:141]
	s_cbranch_vccnz .LBB0_409
	s_ashr_i32 s8, s12, 31
	s_lshr_b32 s8, s8, 29
	s_add_i32 s8, s12, s8
	s_ashr_i32 s9, s8, 3
	s_and_b32 s8, s8, -8
	s_sub_i32 s8, s12, s8
	s_cmp_lt_i32 s8, 0
	s_cselect_b32 s10, s34, 0x68
	s_mul_i32 s8, s8, s10
	s_add_i32 s8, s8, s9
	s_mul_hi_i32 s9, s8, 0x4ec4ec4f
	s_lshr_b32 s10, s9, 31
	s_ashr_i32 s9, s9, 5
	s_add_i32 s9, s9, s10
	s_lshl_b32 s10, s9, 3
	s_sub_i32 s11, 64, s10
	s_min_i32 s11, s11, 8
	s_abs_i32 s12, s11
	v_cvt_f32_u32_e32 v0, s12
	s_sub_i32 s14, 0, s12
	s_mulk_i32 s9, 0x68
	s_sub_i32 s9, s8, s9
	v_rcp_iflag_f32_e32 v0, v0
	s_abs_i32 s8, s9
	s_xor_b32 s13, s9, s11
	s_ashr_i32 s13, s13, 31
	v_mul_f32_e32 v0, 0x4f7ffffe, v0
	v_cvt_u32_f32_e32 v0, v0
	s_nop 0
	v_readfirstlane_b32 s15, v0
	s_mul_i32 s14, s14, s15
	s_mul_hi_u32 s14, s15, s14
	s_add_i32 s15, s15, s14
	s_mul_hi_u32 s14, s8, s15
	s_mul_i32 s15, s14, s12
	s_sub_i32 s8, s8, s15
	s_add_i32 s24, s14, 1
	s_sub_i32 s15, s8, s12
	s_cmp_ge_u32 s8, s12
	s_cselect_b32 s14, s24, s14
	s_cselect_b32 s8, s15, s8
	s_add_i32 s15, s14, 1
	s_cmp_ge_u32 s8, s12
	s_cselect_b32 s8, s15, s14
	s_xor_b32 s8, s8, s13
	s_sub_i32 s8, s8, s13
	s_mul_i32 s11, s8, s11
	s_sub_i32 s9, s9, s11
	s_add_i32 s10, s10, s9

; __device__ __forceinline__ unsigned cvt_pk_bf16(float lo, float hi) { f32x2_t v = {lo, hi}; bf16x2_t b = __builtin_convertvector(v, bf16x2_t); return __builtin_bit_cast(unsigned, b); }
;     __device__ __forceinline__ void operator()(const f32x4 (&acc)[2][2][4][2], const Unit& u, int wr, int wc, int fr, int fq) const {
;     ...
;         bf16_t* base = P + (size_t)t * piece_elems; const int row0 = u.pm * BM + wr * 64 + fr, col0 = colt + wc * 32 + 8 * fq;
; #pragma unroll
;         for (int ai = 0; ai < 2; ++ai)
; #pragma unroll
;             for (int m = 0; m < 4; ++m) { const int row = row0 + ai * HALF + m * 16; bf16_t* rowp = base + (size_t)row * ld + col0;
;                 const float rs = __builtin_amdgcn_rsqf(rowss[row] * (1.0f / 1024.0f) + 1e-6f);
; #pragma unroll
;                 for (int bj = 0; bj < 2; ++bj) { const f32x4 v0 = acc[ai][bj][m][0] * rs, v1 = acc[ai][bj][m][1] * rs; u32x4 w;
;                     w.x = cvt_pk_bf16(v0[0], v0[1]); w.y = cvt_pk_bf16(v0[2], v0[3]); w.z = cvt_pk_bf16(v1[0], v1[1]); w.w = cvt_pk_bf16(v1[2], v1[3]);
;                     *(u32x4*)(rowp + bj * HALF) = w; } }
.LBB0_413:
	v_lshl_add_u32 v144, s16, 8, v152
	v_ashrrev_i32_e32 v145, 31, v144
	v_lshl_add_u64 v[146:147], v[144:145], 2, s[20:21]
	s_min_i32 s11, s45, 12
	s_ashr_i32 s11, s11, 1
	s_lshl_b32 s9, s45, 8
	s_lshl_b32 s16, s11, 9
	s_mul_i32 s18, s11, 0x1040000
	s_sub_i32 s9, s9, s16
	s_mul_hi_i32 s19, s11, 0x1040000
	s_add_u32 s18, s26, s18
	s_addc_u32 s19, s27, s19
	v_or_b32_e32 v148, s9, v154
	s_cmp_eq_u32 s11, 6
	v_ashrrev_i32_e32 v149, 31, v148
	s_cselect_b32 s9, 8, 9
	v_or_b32_e32 v160, 16, v144
	v_lshl_add_u64 v[148:149], v[148:149], 1, s[18:19]
	v_lshlrev_b64 v[166:167], s9, v[144:145]
	v_ashrrev_i32_e32 v161, 31, v160
	v_lshl_add_u64 v[166:167], v[166:167], 1, v[148:149]
	v_lshl_add_u64 v[162:163], v[160:161], 2, s[20:21]
	s_andn2_b64 vcc, exec, s[2:3]
	s_mov_b64 s[2:3], -1
	v_fmamk_f32 v159, v237, 0x3a800000, v158
	v_rsq_f32_e32 v164, v159
	s_nop 0
	v_pk_mul_f32 v[126:127], v[126:127], v[164:165] op_sel_hi:[1,0]
	v_pk_mul_f32 v[124:125], v[124:125], v[164:165] op_sel_hi:[1,0]
	v_pk_mul_f32 v[122:123], v[122:123], v[164:165] op_sel_hi:[1,0]
	v_pk_mul_f32 v[120:121], v[120:121], v[164:165] op_sel_hi:[1,0]
	v_pk_mul_f32 v[118:119], v[118:119], v[164:165] op_sel_hi:[1,0]
	v_pk_mul_f32 v[116:117], v[116:117], v[164:165] op_sel_hi:[1,0]
	v_pk_mul_f32 v[168:169], v[114:115], v[164:165] op_sel_hi:[1,0]
	v_pk_mul_f32 v[164:165], v[112:113], v[164:165] op_sel_hi:[1,0]
	v_cvt_pk_bf16_f32 v112, v124, v125
	v_cvt_pk_bf16_f32 v113, v126, v127
	v_cvt_pk_bf16_f32 v114, v120, v121
	v_cvt_pk_bf16_f32 v115, v122, v123
	v_cvt_pk_bf16_f32 v116, v116, v117
	v_cvt_pk_bf16_f32 v117, v118, v119
	v_cvt_pk_bf16_f32 v118, v164, v165
	v_cvt_pk_bf16_f32 v119, v168, v169
	global_store_dwordx4 v[166:167], v[112:115], off
	global_store_dwordx4 v[166:167], v[116:119], off offset:256
	s_nop 1
	v_or_b32_e32 v112, 32, v144
	v_lshlrev_b64 v[118:119], s9, v[160:161]
	v_ashrrev_i32_e32 v113, 31, v112
	v_lshl_add_u64 v[118:119], v[118:119], 1, v[148:149]
	v_lshl_add_u64 v[116:117], v[112:113], 2, s[20:21]
	v_fmamk_f32 v114, v230, 0x3a800000, v158
	v_rsq_f32_e32 v114, v114
	s_nop 0
	v_pk_mul_f32 v[110:111], v[110:111], v[114:115] op_sel_hi:[1,0]
	v_pk_mul_f32 v[108:109], v[108:109], v[114:115] op_sel_hi:[1,0]
	v_pk_mul_f32 v[106:107], v[106:107], v[114:115] op_sel_hi:[1,0]
	v_pk_mul_f32 v[104:105], v[104:105], v[114:115] op_sel_hi:[1,0]
	v_pk_mul_f32 v[102:103], v[102:103], v[114:115] op_sel_hi:[1,0]
	v_pk_mul_f32 v[100:101], v[100:101], v[114:115] op_sel_hi:[1,0]
	v_pk_mul_f32 v[120:121], v[98:99], v[114:115] op_sel_hi:[1,0]
	v_pk_mul_f32 v[114:115], v[96:97], v[114:115] op_sel_hi:[1,0]
	v_cvt_pk_bf16_f32 v96, v108, v109
	v_cvt_pk_bf16_f32 v97, v110, v111
	v_cvt_pk_bf16_f32 v98, v104, v105
	v_cvt_pk_bf16_f32 v99, v106, v107
	v_cvt_pk_bf16_f32 v100, v100, v101
	v_cvt_pk_bf16_f32 v101, v102, v103
	v_cvt_pk_bf16_f32 v102, v114, v115
	v_cvt_pk_bf16_f32 v103, v120, v121
	global_store_dwordx4 v[118:119], v[96:99], off
	global_store_dwordx4 v[118:119], v[100:103], off offset:256
	s_nop 1
	v_or_b32_e32 v96, 48, v144
	v_lshlrev_b64 v[102:103], s9, v[112:113]
	v_ashrrev_i32_e32 v97, 31, v96
	v_lshl_add_u64 v[102:103], v[102:103], 1, v[148:149]
	v_lshl_add_u64 v[100:101], v[96:97], 2, s[20:21]
	v_fmamk_f32 v98, v231, 0x3a800000, v158
	v_rsq_f32_e32 v98, v98
	s_nop 0
	v_pk_mul_f32 v[94:95], v[94:95], v[98:99] op_sel_hi:[1,0]
	v_pk_mul_f32 v[92:93], v[92:93], v[98:99] op_sel_hi:[1,0]
	v_pk_mul_f32 v[90:91], v[90:91], v[98:99] op_sel_hi:[1,0]
	v_pk_mul_f32 v[88:89], v[88:89], v[98:99] op_sel_hi:[1,0]
	v_pk_mul_f32 v[82:83], v[82:83], v[98:99] op_sel_hi:[1,0]
	v_pk_mul_f32 v[80:81], v[80:81], v[98:99] op_sel_hi:[1,0]
	v_pk_mul_f32 v[104:105], v[74:75], v[98:99] op_sel_hi:[1,0]
	v_pk_mul_f32 v[98:99], v[72:73], v[98:99] op_sel_hi:[1,0]
	v_cvt_pk_bf16_f32 v72, v92, v93
	v_cvt_pk_bf16_f32 v73, v94, v95
	v_cvt_pk_bf16_f32 v74, v88, v89
	v_cvt_pk_bf16_f32 v75, v90, v91
	v_cvt_pk_bf16_f32 v80, v80, v81
	v_cvt_pk_bf16_f32 v81, v82, v83
	v_cvt_pk_bf16_f32 v82, v98, v99
	v_cvt_pk_bf16_f32 v83, v104, v105
	global_store_dwordx4 v[102:103], v[72:75], off
	global_store_dwordx4 v[102:103], v[80:83], off offset:256
	s_nop 1
	v_lshlrev_b64 v[74:75], s9, v[96:97]
	v_lshl_add_u64 v[74:75], v[74:75], 1, v[148:149]
	v_fmamk_f32 v72, v232, 0x3a800000, v158
	v_rsq_f32_e32 v72, v72
	s_nop 0
	v_pk_mul_f32 v[80:81], v[86:87], v[72:73] op_sel_hi:[1,0]
	v_pk_mul_f32 v[82:83], v[84:85], v[72:73] op_sel_hi:[1,0]
	v_pk_mul_f32 v[78:79], v[78:79], v[72:73] op_sel_hi:[1,0]
	v_pk_mul_f32 v[76:77], v[76:77], v[72:73] op_sel_hi:[1,0]
	v_pk_mul_f32 v[70:71], v[70:71], v[72:73] op_sel_hi:[1,0]
	v_pk_mul_f32 v[68:69], v[68:69], v[72:73] op_sel_hi:[1,0]
	v_pk_mul_f32 v[84:85], v[66:67], v[72:73] op_sel_hi:[1,0]
	v_pk_mul_f32 v[72:73], v[64:65], v[72:73] op_sel_hi:[1,0]
; __device__ __forceinline__ unsigned cvt_pk_bf16(float lo, float hi) { f32x2_t v = {lo, hi}; bf16x2_t b = __builtin_convertvector(v, bf16x2_t); return __builtin_bit_cast(unsigned, b); }
; #define PG8_BAR __builtin_amdgcn_s_barrier()
;     __device__ __forceinline__ void operator()(const f32x4 (&acc)[2][2][4][2], const Unit& u, int wr, int wc, int fr, int fq) const {
;     ...
;             for (int m = 0; m < 4; ++m) { const int row = row0 + ai * HALF + m * 16; bf16_t* rowp = base + (size_t)row * ld + col0;
;                 const float rs = __builtin_amdgcn_rsqf(rowss[row] * (1.0f / 1024.0f) + 1e-6f);
; #pragma unroll
;                 for (int bj = 0; bj < 2; ++bj) { const f32x4 v0 = acc[ai][bj][m][0] * rs, v1 = acc[ai][bj][m][1] * rs; u32x4 w;
;                     w.x = cvt_pk_bf16(v0[0], v0[1]); w.y = cvt_pk_bf16(v0[2], v0[3]); w.z = cvt_pk_bf16(v1[0], v1[1]); w.w = cvt_pk_bf16(v1[2], v1[3]);
;                     *(u32x4*)(rowp + bj * HALF) = w; } }
; template <class Epi, class Sched, bool ALIGN_EPI = false, bool SP2 = false>
; __device__ __forceinline__ void gemm_phase(PG8_LAS unsigned char* lds, const Gemm g, const Sched& S, const Epi& E) {
;     ...
;         if (!has_next) break;
; #pragma unroll
;         for (int a = 0; a < 2; ++a)
; #pragma unroll
;             for (int b = 0; b < 2; ++b)
; #pragma unroll
;                 for (int m = 0; m < 4; ++m)
; #pragma unroll
;                     for (int n = 0; n < 2; ++n) acc[a][b][m][n] = (f32x4){0.f, 0.f, 0.f, 0.f};
;         cur = nxt; cA = nA; cB = nB; ++ui;
;         if constexpr (ALIGN_EPI) { if (wr == 1) PG8_BAR; }
	v_cvt_pk_bf16_f32 v64, v82, v83
	v_cvt_pk_bf16_f32 v65, v80, v81
	v_cvt_pk_bf16_f32 v66, v76, v77
	v_cvt_pk_bf16_f32 v67, v78, v79
	v_cvt_pk_bf16_f32 v68, v68, v69
	v_cvt_pk_bf16_f32 v69, v70, v71
	v_cvt_pk_bf16_f32 v70, v72, v73
	v_cvt_pk_bf16_f32 v71, v84, v85
	global_store_dwordx4 v[74:75], v[64:67], off
	global_store_dwordx4 v[74:75], v[68:71], off offset:256
	s_nop 1
	v_add_u32_e32 v64, 0x80, v144
	v_fmamk_f32 v65, v233, 0x3a800000, v158
	v_rsq_f32_e32 v66, v65
	v_ashrrev_i32_e32 v65, 31, v64
	v_lshlrev_b64 v[64:65], s9, v[64:65]
	v_lshl_add_u64 v[64:65], v[64:65], 1, v[148:149]
	v_pk_mul_f32 v[62:63], v[62:63], v[66:67] op_sel_hi:[1,0]
	v_pk_mul_f32 v[60:61], v[60:61], v[66:67] op_sel_hi:[1,0]
	v_pk_mul_f32 v[58:59], v[58:59], v[66:67] op_sel_hi:[1,0]
	v_pk_mul_f32 v[56:57], v[56:57], v[66:67] op_sel_hi:[1,0]
	v_pk_mul_f32 v[54:55], v[54:55], v[66:67] op_sel_hi:[1,0]
	v_pk_mul_f32 v[52:53], v[52:53], v[66:67] op_sel_hi:[1,0]
	v_pk_mul_f32 v[68:69], v[50:51], v[66:67] op_sel_hi:[1,0]
	v_pk_mul_f32 v[66:67], v[48:49], v[66:67] op_sel_hi:[1,0]
	v_cvt_pk_bf16_f32 v48, v60, v61
	v_cvt_pk_bf16_f32 v49, v62, v63
	v_cvt_pk_bf16_f32 v50, v56, v57
	v_cvt_pk_bf16_f32 v51, v58, v59
	v_cvt_pk_bf16_f32 v52, v52, v53
	v_cvt_pk_bf16_f32 v53, v54, v55
	v_cvt_pk_bf16_f32 v54, v66, v67
	v_cvt_pk_bf16_f32 v55, v68, v69
	global_store_dwordx4 v[64:65], v[48:51], off
	global_store_dwordx4 v[64:65], v[52:55], off offset:256
	s_nop 1
	v_add_u32_e32 v48, 0x90, v144
	v_fmamk_f32 v49, v234, 0x3a800000, v158
	v_rsq_f32_e32 v50, v49
	v_ashrrev_i32_e32 v49, 31, v48
	v_lshlrev_b64 v[48:49], s9, v[48:49]
	v_lshl_add_u64 v[48:49], v[48:49], 1, v[148:149]
	v_pk_mul_f32 v[46:47], v[46:47], v[50:51] op_sel_hi:[1,0]
	v_pk_mul_f32 v[44:45], v[44:45], v[50:51] op_sel_hi:[1,0]
	v_pk_mul_f32 v[42:43], v[42:43], v[50:51] op_sel_hi:[1,0]
	v_pk_mul_f32 v[40:41], v[40:41], v[50:51] op_sel_hi:[1,0]
	v_pk_mul_f32 v[38:39], v[38:39], v[50:51] op_sel_hi:[1,0]
	v_pk_mul_f32 v[36:37], v[36:37], v[50:51] op_sel_hi:[1,0]
	v_pk_mul_f32 v[52:53], v[34:35], v[50:51] op_sel_hi:[1,0]
	v_pk_mul_f32 v[50:51], v[32:33], v[50:51] op_sel_hi:[1,0]
	v_cvt_pk_bf16_f32 v32, v44, v45
	v_cvt_pk_bf16_f32 v33, v46, v47
	v_cvt_pk_bf16_f32 v34, v40, v41
	v_cvt_pk_bf16_f32 v35, v42, v43
	v_cvt_pk_bf16_f32 v36, v36, v37
	v_cvt_pk_bf16_f32 v37, v38, v39
	v_cvt_pk_bf16_f32 v38, v50, v51
	v_cvt_pk_bf16_f32 v39, v52, v53
	global_store_dwordx4 v[48:49], v[32:35], off
	global_store_dwordx4 v[48:49], v[36:39], off offset:256
	s_nop 1
	v_add_u32_e32 v32, 0xa0, v144
	v_fmamk_f32 v33, v235, 0x3a800000, v158
	v_rsq_f32_e32 v34, v33
	v_ashrrev_i32_e32 v33, 31, v32
	v_lshlrev_b64 v[32:33], s9, v[32:33]
	v_lshl_add_u64 v[32:33], v[32:33], 1, v[148:149]
	v_pk_mul_f32 v[30:31], v[30:31], v[34:35] op_sel_hi:[1,0]
	v_pk_mul_f32 v[28:29], v[28:29], v[34:35] op_sel_hi:[1,0]
	v_pk_mul_f32 v[26:27], v[26:27], v[34:35] op_sel_hi:[1,0]
	v_pk_mul_f32 v[24:25], v[24:25], v[34:35] op_sel_hi:[1,0]
	v_pk_mul_f32 v[22:23], v[22:23], v[34:35] op_sel_hi:[1,0]
	v_pk_mul_f32 v[20:21], v[20:21], v[34:35] op_sel_hi:[1,0]
	v_pk_mul_f32 v[36:37], v[18:19], v[34:35] op_sel_hi:[1,0]
	v_pk_mul_f32 v[34:35], v[16:17], v[34:35] op_sel_hi:[1,0]
	v_cvt_pk_bf16_f32 v16, v28, v29
	v_cvt_pk_bf16_f32 v17, v30, v31
	v_cvt_pk_bf16_f32 v18, v24, v25
	v_cvt_pk_bf16_f32 v19, v26, v27
	v_cvt_pk_bf16_f32 v20, v20, v21
	v_cvt_pk_bf16_f32 v21, v22, v23
	v_cvt_pk_bf16_f32 v22, v34, v35
	v_cvt_pk_bf16_f32 v23, v36, v37
	global_store_dwordx4 v[32:33], v[16:19], off
	global_store_dwordx4 v[32:33], v[20:23], off offset:256
	s_nop 1
	v_add_u32_e32 v16, 0xb0, v144
	v_ashrrev_i32_e32 v17, 31, v16
	v_lshlrev_b64 v[16:17], s9, v[16:17]
	v_lshl_add_u64 v[16:17], v[16:17], 1, v[148:149]
	v_fmamk_f32 v18, v236, 0x3a800000, v158
	v_rsq_f32_e32 v18, v18
	s_nop 0
	v_pk_mul_f32 v[14:15], v[14:15], v[18:19] op_sel_hi:[1,0]
	v_pk_mul_f32 v[12:13], v[12:13], v[18:19] op_sel_hi:[1,0]
	v_pk_mul_f32 v[10:11], v[10:11], v[18:19] op_sel_hi:[1,0]
	v_pk_mul_f32 v[8:9], v[8:9], v[18:19] op_sel_hi:[1,0]
	v_pk_mul_f32 v[6:7], v[6:7], v[18:19] op_sel_hi:[1,0]
	v_pk_mul_f32 v[4:5], v[4:5], v[18:19] op_sel_hi:[1,0]
	v_pk_mul_f32 v[20:21], v[2:3], v[18:19] op_sel_hi:[1,0]
	v_pk_mul_f32 v[18:19], v[0:1], v[18:19] op_sel_hi:[1,0]
	v_cvt_pk_bf16_f32 v0, v12, v13
	v_cvt_pk_bf16_f32 v1, v14, v15
	v_cvt_pk_bf16_f32 v2, v8, v9
	v_cvt_pk_bf16_f32 v3, v10, v11
	v_cvt_pk_bf16_f32 v4, v4, v5
	v_cvt_pk_bf16_f32 v5, v6, v7
	v_cvt_pk_bf16_f32 v6, v18, v19
	v_cvt_pk_bf16_f32 v7, v20, v21
	global_store_dwordx4 v[16:17], v[0:3], off
	global_store_dwordx4 v[16:17], v[4:7], off offset:256
	s_cbranch_vccnz .LBB0_406
	s_andn2_b64 vcc, exec, s[0:1]
	s_cbranch_vccnz .LBB0_405
	s_barrier
	s_branch .LBB0_405
